# grid barrier: waiting workgroups poll the cross-XCD release word directly (one hop fewer)
# baseline (speedup 1.0000x reference)
; __device__ __forceinline__ unsigned xb_ld(unsigned* p)              { return __hip_atomic_load(p, __ATOMIC_RELAXED, __HIP_MEMORY_SCOPE_AGENT); }
; __device__ __forceinline__ unsigned xb_add(unsigned* p, unsigned v) { return __hip_atomic_fetch_add(p, v, __ATOMIC_RELAXED, __HIP_MEMORY_SCOPE_AGENT); }
; #define XB_SPIN(cond, bar) do { unsigned _sp = 0; while (cond) { __builtin_amdgcn_s_sleep(1); \
;     if ((++_sp & 255u) == 0u) { if (xb_ld(&(bar)[XB_TMO])) break; if (_sp > XB_SPIN_CAP) { atomicAdd(&(bar)[XB_TMO], 1u); break; } } } } while (0)
; __device__ __forceinline__ void xcd_barrier(const XcdBarrier& b) {
;     ...
;         const unsigned old = xb_add(&bar[XB_XSUB(b.x)], 1u);
;         const unsigned gen = old / nloc;
;         if (old + 1u == (gen + 1u) * nloc) {
;     ...
;         } else {
;             XB_SPIN(xb_ld(&bar[XB_XGEN(b.x)]) == gen, bar);
.LBB0_137:
	v_readlane_b32 s2, v253, 11
	v_readlane_b32 s3, v253, 12
	v_cvt_f32_u32_e32 v0, v2
	v_sub_u32_e32 v4, 0, v2
	v_rcp_iflag_f32_e32 v0, v0
	s_nop 1
	global_atomic_add v3, v129, v207, s[2:3] sc0
	v_mul_f32_e32 v0, 0x4f7ffffe, v0
	v_cvt_u32_f32_e32 v0, v0
	v_mul_lo_u32 v4, v4, v0
	v_mul_hi_u32 v4, v0, v4
	v_add_u32_e32 v0, v0, v4
	s_waitcnt vmcnt(0)
	v_mul_hi_u32 v0, v3, v0
	v_mul_lo_u32 v4, v0, v2
	v_sub_u32_e32 v4, v3, v4
	v_add_u32_e32 v5, 1, v0
	v_cmp_ge_u32_e32 vcc, v4, v2
	v_add_u32_e32 v3, 1, v3
	s_nop 0
	v_cndmask_b32_e32 v0, v0, v5, vcc
	v_sub_u32_e32 v5, v4, v2
	v_cndmask_b32_e32 v4, v4, v5, vcc
	v_add_u32_e32 v5, 1, v0
	v_cmp_ge_u32_e32 vcc, v4, v2
	s_nop 1
	v_cndmask_b32_e32 v0, v0, v5, vcc
	v_mul_lo_u32 v4, v2, v0
	v_add_u32_e32 v2, v4, v2
	v_cmp_ne_u32_e32 vcc, v3, v2
	s_and_saveexec_b64 s[2:3], vcc
	s_xor_b64 s[2:3], exec, s[2:3]
	s_cbranch_execz .LBB0_151
	v_readlane_b32 s6, v253, 17
	v_readlane_b32 s7, v253, 18
	s_waitcnt lgkmcnt(0)
	s_nop 3
	global_load_dword v1, v129, s[6:7] sc1
	s_waitcnt vmcnt(0)
	v_cmp_eq_u32_e32 vcc, v1, v0
	s_and_saveexec_b64 s[6:7], vcc
	s_cbranch_execz .LBB0_150
	s_mov_b32 s19, 1
	s_mov_b64 s[8:9], 0
	s_branch .LBB0_141

; __device__ __forceinline__ unsigned xb_ld(unsigned* p)              { return __hip_atomic_load(p, __ATOMIC_RELAXED, __HIP_MEMORY_SCOPE_AGENT); }
; #define XB_SPIN(cond, bar) do { unsigned _sp = 0; while (cond) { __builtin_amdgcn_s_sleep(1); \
;     if ((++_sp & 255u) == 0u) { if (xb_ld(&(bar)[XB_TMO])) break; if (_sp > XB_SPIN_CAP) { atomicAdd(&(bar)[XB_TMO], 1u); break; } } } } while (0)
; __device__ __forceinline__ void xcd_barrier(const XcdBarrier& b) {
;     ...
;             XB_SPIN(xb_ld(&bar[XB_XGEN(b.x)]) == gen, bar);
.LBB0_145:
	v_readlane_b32 s12, v253, 17
	v_readlane_b32 s13, v253, 18
	s_add_i32 s19, s19, 1
	s_mov_b64 s[14:15], -1
	s_nop 2
	global_load_dword v1, v129, s[12:13] sc1
	s_waitcnt vmcnt(0)
	v_cmp_ne_u32_e32 vcc, v1, v0
	s_orn2_b64 s[12:13], vcc, exec
	s_branch .LBB0_140

; __device__ __forceinline__ unsigned xb_ld(unsigned* p)              { return __hip_atomic_load(p, __ATOMIC_RELAXED, __HIP_MEMORY_SCOPE_AGENT); }
; __device__ __forceinline__ unsigned xb_add(unsigned* p, unsigned v) { return __hip_atomic_fetch_add(p, v, __ATOMIC_RELAXED, __HIP_MEMORY_SCOPE_AGENT); }
; #define XB_SPIN(cond, bar) do { unsigned _sp = 0; while (cond) { __builtin_amdgcn_s_sleep(1); \
;     if ((++_sp & 255u) == 0u) { if (xb_ld(&(bar)[XB_TMO])) break; if (_sp > XB_SPIN_CAP) { atomicAdd(&(bar)[XB_TMO], 1u); break; } } } } while (0)
; __device__ __forceinline__ void xcd_barrier(const XcdBarrier& b) {
;     ...
;         const unsigned old = xb_add(&bar[XB_XSUB(b.x)], 1u);
;         const unsigned gen = old / nloc;
;         if (old + 1u == (gen + 1u) * nloc) {
;     ...
;         } else {
;             XB_SPIN(xb_ld(&bar[XB_XGEN(b.x)]) == gen, bar);
.LBB0_193:
	v_readlane_b32 s2, v253, 11
	v_readlane_b32 s3, v253, 12
	v_cvt_f32_u32_e32 v1, v2
	v_sub_u32_e32 v4, 0, v2
	v_rcp_iflag_f32_e32 v1, v1
	s_nop 1
	global_atomic_add v3, v129, v207, s[2:3] sc0
	v_mul_f32_e32 v1, 0x4f7ffffe, v1
	v_cvt_u32_f32_e32 v1, v1
	v_mul_lo_u32 v4, v4, v1
	v_mul_hi_u32 v4, v1, v4
	v_add_u32_e32 v1, v1, v4
	s_waitcnt vmcnt(0)
	v_mul_hi_u32 v1, v3, v1
	v_mul_lo_u32 v4, v1, v2
	v_sub_u32_e32 v4, v3, v4
	v_add_u32_e32 v5, 1, v1
	v_cmp_ge_u32_e32 vcc, v4, v2
	v_add_u32_e32 v3, 1, v3
	s_nop 0
	v_cndmask_b32_e32 v1, v1, v5, vcc
	v_sub_u32_e32 v5, v4, v2
	v_cndmask_b32_e32 v4, v4, v5, vcc
	v_add_u32_e32 v5, 1, v1
	v_cmp_ge_u32_e32 vcc, v4, v2
	s_nop 1
	v_cndmask_b32_e32 v1, v1, v5, vcc
	v_mul_lo_u32 v4, v2, v1
	v_add_u32_e32 v2, v4, v2
	v_cmp_ne_u32_e32 vcc, v3, v2
	s_and_saveexec_b64 s[2:3], vcc
	s_xor_b64 s[2:3], exec, s[2:3]
	s_cbranch_execz .LBB0_207
	v_readlane_b32 s4, v253, 17
	v_readlane_b32 s5, v253, 18
	s_waitcnt lgkmcnt(0)
	s_nop 3
	global_load_dword v0, v129, s[4:5] sc1
	s_waitcnt vmcnt(0)
	v_cmp_eq_u32_e32 vcc, v0, v1
	s_and_saveexec_b64 s[4:5], vcc
	s_cbranch_execz .LBB0_206
	s_mov_b32 s16, 1
	s_mov_b64 s[6:7], 0
	s_branch .LBB0_197

; __device__ __forceinline__ unsigned xb_ld(unsigned* p)              { return __hip_atomic_load(p, __ATOMIC_RELAXED, __HIP_MEMORY_SCOPE_AGENT); }
; #define XB_SPIN(cond, bar) do { unsigned _sp = 0; while (cond) { __builtin_amdgcn_s_sleep(1); \
;     if ((++_sp & 255u) == 0u) { if (xb_ld(&(bar)[XB_TMO])) break; if (_sp > XB_SPIN_CAP) { atomicAdd(&(bar)[XB_TMO], 1u); break; } } } } while (0)
; __device__ __forceinline__ void xcd_barrier(const XcdBarrier& b) {
;     ...
;             XB_SPIN(xb_ld(&bar[XB_XGEN(b.x)]) == gen, bar);
.LBB0_201:
	v_readlane_b32 s10, v253, 17
	v_readlane_b32 s11, v253, 18
	s_add_i32 s16, s16, 1
	s_mov_b64 s[12:13], -1
	s_nop 2
	global_load_dword v0, v129, s[10:11] sc1
	s_waitcnt vmcnt(0)
	v_cmp_ne_u32_e32 vcc, v0, v1
	s_orn2_b64 s[10:11], vcc, exec
	s_branch .LBB0_196

; __device__ __forceinline__ unsigned xb_ld(unsigned* p)              { return __hip_atomic_load(p, __ATOMIC_RELAXED, __HIP_MEMORY_SCOPE_AGENT); }
; __device__ __forceinline__ unsigned xb_add(unsigned* p, unsigned v) { return __hip_atomic_fetch_add(p, v, __ATOMIC_RELAXED, __HIP_MEMORY_SCOPE_AGENT); }
; #define XB_SPIN(cond, bar) do { unsigned _sp = 0; while (cond) { __builtin_amdgcn_s_sleep(1); \
;     if ((++_sp & 255u) == 0u) { if (xb_ld(&(bar)[XB_TMO])) break; if (_sp > XB_SPIN_CAP) { atomicAdd(&(bar)[XB_TMO], 1u); break; } } } } while (0)
; __device__ __forceinline__ void xcd_barrier(const XcdBarrier& b) {
;     ...
;         const unsigned old = xb_add(&bar[XB_XSUB(b.x)], 1u);
;         const unsigned gen = old / nloc;
;         if (old + 1u == (gen + 1u) * nloc) {
;     ...
;         } else {
;             XB_SPIN(xb_ld(&bar[XB_XGEN(b.x)]) == gen, bar);
.LBB0_314:
	v_readlane_b32 s2, v253, 11
	v_readlane_b32 s3, v253, 12
	v_cvt_f32_u32_e32 v1, v2
	v_sub_u32_e32 v4, 0, v2
	v_rcp_iflag_f32_e32 v1, v1
	s_nop 1
	global_atomic_add v3, v129, v207, s[2:3] sc0
	v_mul_f32_e32 v1, 0x4f7ffffe, v1
	v_cvt_u32_f32_e32 v1, v1
	v_mul_lo_u32 v4, v4, v1
	v_mul_hi_u32 v4, v1, v4
	v_add_u32_e32 v1, v1, v4
	s_waitcnt vmcnt(0)
	v_mul_hi_u32 v1, v3, v1
	v_mul_lo_u32 v4, v1, v2
	v_sub_u32_e32 v4, v3, v4
	v_add_u32_e32 v5, 1, v1
	v_cmp_ge_u32_e32 vcc, v4, v2
	v_add_u32_e32 v3, 1, v3
	s_nop 0
	v_cndmask_b32_e32 v1, v1, v5, vcc
	v_sub_u32_e32 v5, v4, v2
	v_cndmask_b32_e32 v4, v4, v5, vcc
	v_add_u32_e32 v5, 1, v1
	v_cmp_ge_u32_e32 vcc, v4, v2
	s_nop 1
	v_cndmask_b32_e32 v1, v1, v5, vcc
	v_mul_lo_u32 v4, v2, v1
	v_add_u32_e32 v2, v4, v2
	v_cmp_ne_u32_e32 vcc, v3, v2
	s_and_saveexec_b64 s[2:3], vcc
	s_xor_b64 s[2:3], exec, s[2:3]
	s_cbranch_execz .LBB0_328
	v_readlane_b32 s4, v253, 17
	v_readlane_b32 s5, v253, 18
	s_waitcnt lgkmcnt(0)
	s_nop 3
	global_load_dword v0, v129, s[4:5] sc1
	s_waitcnt vmcnt(0)
	v_cmp_eq_u32_e32 vcc, v0, v1
	s_and_saveexec_b64 s[4:5], vcc
	s_cbranch_execz .LBB0_327
	s_mov_b32 s17, 1
	s_mov_b64 s[6:7], 0
	s_branch .LBB0_318

; __device__ __forceinline__ unsigned xb_ld(unsigned* p)              { return __hip_atomic_load(p, __ATOMIC_RELAXED, __HIP_MEMORY_SCOPE_AGENT); }
; #define XB_SPIN(cond, bar) do { unsigned _sp = 0; while (cond) { __builtin_amdgcn_s_sleep(1); \
;     if ((++_sp & 255u) == 0u) { if (xb_ld(&(bar)[XB_TMO])) break; if (_sp > XB_SPIN_CAP) { atomicAdd(&(bar)[XB_TMO], 1u); break; } } } } while (0)
; __device__ __forceinline__ void xcd_barrier(const XcdBarrier& b) {
;     ...
;             XB_SPIN(xb_ld(&bar[XB_XGEN(b.x)]) == gen, bar);
.LBB0_322:
	v_readlane_b32 s10, v253, 17
	v_readlane_b32 s11, v253, 18
	s_add_i32 s17, s17, 1
	s_mov_b64 s[12:13], -1
	s_nop 2
	global_load_dword v0, v129, s[10:11] sc1
	s_waitcnt vmcnt(0)
	v_cmp_ne_u32_e32 vcc, v0, v1
	s_orn2_b64 s[10:11], vcc, exec
	s_branch .LBB0_317
